# final RMSNorm phase: 4 rows batched per wave iteration (16 loads in flight) + sg_post loads hoisted
# baseline (speedup 1.0000x reference)
.LBB0_1471:
	v_readlane_b32 s0, v252, 0
	v_ashrrev_i32_e32 v0, 6, v232
	s_nop 0
	v_lshl_add_u32 v16, s0, 3, v0
	s_mov_b32 s0, 0x8000
	v_cmp_gt_i32_e32 vcc, s0, v16
	s_and_saveexec_b64 s[0:1], vcc
	s_cbranch_execz .LBB0_1474
	v_lshlrev_b32_e32 v0, 2, v232
	v_and_b32_e32 v17, 0xfc, v0
	v_lshlrev_b32_e32 v18, 2, v17
	global_load_dwordx4 v[0:3], v18, s[78:79]
	global_load_dwordx4 v[4:7], v18, s[78:79] offset:1024
	global_load_dwordx4 v[8:11], v18, s[78:79] offset:2048
	global_load_dwordx4 v[12:15], v18, s[78:79] offset:3072
	v_cmp_lt_i32_e32 vcc, v246, v240
	s_lshl_b32 s0, s62, 3
	v_mov_b32_e32 v19, 0
	v_cndmask_b32_e32 v18, v239, v246, vcc
	v_cmp_lt_i32_e32 vcc, v245, v240
	v_lshlrev_b32_e32 v24, 2, v18
	s_ashr_i32 s1, s0, 31
	v_cndmask_b32_e32 v18, v239, v245, vcc
	v_cmp_lt_i32_e32 vcc, v244, v240
	v_lshlrev_b32_e32 v25, 2, v18
	v_mov_b32_e32 v21, v19
	v_cndmask_b32_e32 v18, v239, v244, vcc
	v_cmp_lt_i32_e32 vcc, v243, v240
	v_lshlrev_b32_e32 v26, 2, v18
	s_lshl_b64 s[2:3], s[0:1], 12
	v_cndmask_b32_e32 v18, v239, v243, vcc
	v_cmp_lt_i32_e32 vcc, v242, v240
	v_lshlrev_b32_e32 v27, 2, v18
	s_mov_b64 s[4:5], 0
	v_cndmask_b32_e32 v18, v239, v242, vcc
	v_cmp_lt_i32_e32 vcc, v241, v240
	v_lshlrev_b32_e32 v28, 2, v18
	s_mov_b32 s1, 0x800000
	v_cndmask_b32_e32 v18, v239, v241, vcc
	v_lshlrev_b32_e32 v29, 2, v18
	v_lshlrev_b32_e32 v18, 1, v17
	v_and_b32_e32 v17, 63, v232
	v_lshlrev_b32_e32 v20, 4, v17
	v_ashrrev_i32_e32 v17, 31, v16
	v_lshlrev_b64 v[22:23], 12, v[16:17]
	v_lshl_add_u64 v[22:23], s[80:81], 0, v[22:23]
	v_mov_b32_e32 v17, 0x358637bd
	s_movk_i32 s6, 0x7fff
	v_readfirstlane_b32 s8, v16
.Lfin_fast:
	s_mul_i32 s9, s0, 3
	s_add_i32 s9, s9, s8
	s_cmp_lt_i32 s9, 0x8000
	s_cbranch_scc0 .Lfin_tail
	v_lshl_add_u64 v[92:93], v[22:23], 0, v[18:19]
	global_load_dwordx2 v[60:61], v[92:93], off offset:512
	global_load_dwordx2 v[62:63], v[92:93], off
	global_load_dwordx2 v[64:65], v[92:93], off offset:1536
	global_load_dwordx2 v[66:67], v[92:93], off offset:1024
	v_lshl_add_u64 v[92:93], v[92:93], 0, s[2:3]
	global_load_dwordx2 v[68:69], v[92:93], off offset:512
	global_load_dwordx2 v[70:71], v[92:93], off
	global_load_dwordx2 v[72:73], v[92:93], off offset:1536
	global_load_dwordx2 v[74:75], v[92:93], off offset:1024
	v_lshl_add_u64 v[92:93], v[92:93], 0, s[2:3]
	global_load_dwordx2 v[76:77], v[92:93], off offset:512
	global_load_dwordx2 v[78:79], v[92:93], off
	global_load_dwordx2 v[80:81], v[92:93], off offset:1536
	global_load_dwordx2 v[82:83], v[92:93], off offset:1024
	v_lshl_add_u64 v[92:93], v[92:93], 0, s[2:3]
	global_load_dwordx2 v[84:85], v[92:93], off offset:512
	global_load_dwordx2 v[86:87], v[92:93], off
	global_load_dwordx2 v[88:89], v[92:93], off offset:1536
	global_load_dwordx2 v[90:91], v[92:93], off offset:1024
	s_waitcnt vmcnt(12)
	v_mov_b64_e32 v[32:33], v[60:61]
	v_mov_b64_e32 v[34:35], v[62:63]
	v_mov_b64_e32 v[36:37], v[64:65]
	v_mov_b64_e32 v[38:39], v[66:67]
	v_lshl_add_u64 v[46:47], v[22:23], 0, v[20:21]
	v_lshl_add_u64 v[22:23], v[22:23], 0, s[2:3]
	v_and_b32_e32 v41, 0xffff0000, v32
	v_and_b32_e32 v40, 0xffff0000, v34
	v_lshlrev_b32_e32 v31, 16, v32
	v_lshlrev_b32_e32 v30, 16, v34
	v_lshlrev_b32_e32 v42, 16, v35
	v_and_b32_e32 v32, 0xffff0000, v35
	v_lshlrev_b32_e32 v35, 16, v36
	v_lshlrev_b32_e32 v34, 16, v38
	v_and_b32_e32 v45, 0xffff0000, v36
	v_and_b32_e32 v44, 0xffff0000, v38
	v_lshlrev_b32_e32 v48, 16, v39
	v_and_b32_e32 v36, 0xffff0000, v39
	v_pk_mul_f32 v[38:39], v[40:41], v[40:41]
	v_lshlrev_b32_e32 v43, 16, v33
	v_pk_mul_f32 v[50:51], v[44:45], v[44:45]
	v_mov_b32_e32 v52, v30
	v_mov_b32_e32 v53, v40
	v_mov_b32_e32 v40, v31
	v_pk_fma_f32 v[30:31], v[30:31], v[30:31], v[38:39]
	v_and_b32_e32 v33, 0xffff0000, v33
	v_lshlrev_b32_e32 v49, 16, v37
	v_mov_b32_e32 v56, v34
	v_mov_b32_e32 v57, v44
	v_mov_b32_e32 v44, v35
	v_pk_fma_f32 v[34:35], v[34:35], v[34:35], v[50:51]
	v_pk_fma_f32 v[30:31], v[42:43], v[42:43], v[30:31]
	v_and_b32_e32 v37, 0xffff0000, v37
	v_pk_fma_f32 v[34:35], v[48:49], v[48:49], v[34:35]
	v_pk_fma_f32 v[30:31], v[32:33], v[32:33], v[30:31]
	v_pk_fma_f32 v[34:35], v[36:37], v[36:37], v[34:35]
	v_add_f32_e32 v30, v30, v31
	v_add_f32_e32 v30, v30, v34
	v_add_f32_e32 v30, v30, v35
	ds_bpermute_b32 v31, v24, v30
	v_mov_b32_e32 v54, v42
	v_mov_b32_e32 v55, v32
	v_mov_b32_e32 v58, v48
	v_mov_b32_e32 v59, v36
	s_waitcnt lgkmcnt(0)
	v_add_f32_e32 v30, v30, v31
	ds_bpermute_b32 v31, v25, v30
	v_mov_b32_e32 v32, v43
	v_mov_b32_e32 v36, v49
	s_waitcnt lgkmcnt(0)
	v_add_f32_e32 v30, v30, v31
	ds_bpermute_b32 v31, v26, v30
	s_waitcnt lgkmcnt(0)
	v_add_f32_e32 v30, v30, v31
	ds_bpermute_b32 v31, v27, v30
	s_waitcnt lgkmcnt(0)
	v_add_f32_e32 v30, v30, v31
	ds_bpermute_b32 v31, v28, v30
	s_waitcnt lgkmcnt(0)
	v_add_f32_e32 v30, v30, v31
	ds_bpermute_b32 v31, v29, v30
	s_waitcnt lgkmcnt(0)
	v_add_f32_e32 v30, v30, v31
	v_fmamk_f32 v30, v30, 0x3a800000, v17
	v_mul_f32_e32 v31, 0x4b800000, v30
	v_cmp_gt_f32_e32 vcc, s1, v30
	s_nop 1
	v_cndmask_b32_e32 v30, v30, v31, vcc
	v_rsq_f32_e32 v30, v30
	s_nop 0
	v_mul_f32_e32 v31, 0x45800000, v30
	v_cndmask_b32_e32 v30, v30, v31, vcc
	v_pk_mul_f32 v[34:35], v[52:53], v[30:31] op_sel_hi:[1,0]
	v_pk_mul_f32 v[38:39], v[54:55], v[30:31] op_sel_hi:[1,0]
	v_pk_mul_f32 v[40:41], v[40:41], v[30:31] op_sel_hi:[1,0]
	v_pk_mul_f32 v[42:43], v[32:33], v[30:31] op_sel_hi:[1,0]
	v_pk_mul_f32 v[48:49], v[56:57], v[30:31] op_sel_hi:[1,0]
	v_pk_mul_f32 v[50:51], v[58:59], v[30:31] op_sel_hi:[1,0]
	v_pk_mul_f32 v[52:53], v[44:45], v[30:31] op_sel_hi:[1,0]
	v_pk_mul_f32 v[44:45], v[36:37], v[30:31] op_sel_hi:[1,0]
	v_pk_mul_f32 v[32:33], v[2:3], v[38:39]
	v_pk_mul_f32 v[30:31], v[0:1], v[34:35]
	v_pk_mul_f32 v[36:37], v[6:7], v[42:43]
	v_pk_mul_f32 v[34:35], v[4:5], v[40:41]
	v_pk_mul_f32 v[40:41], v[10:11], v[50:51]
	v_pk_mul_f32 v[38:39], v[8:9], v[48:49]
	v_pk_mul_f32 v[44:45], v[14:15], v[44:45]
	v_pk_mul_f32 v[42:43], v[12:13], v[52:53]
	global_store_dwordx4 v[46:47], v[30:33], off
	global_store_dwordx4 v[46:47], v[34:37], off offset:1024
	global_store_dwordx4 v[46:47], v[38:41], off offset:2048
	global_store_dwordx4 v[46:47], v[42:45], off offset:3072
	s_nop 1
	s_waitcnt vmcnt(12)
	v_mov_b64_e32 v[32:33], v[68:69]
	v_mov_b64_e32 v[34:35], v[70:71]
	v_mov_b64_e32 v[36:37], v[72:73]
	v_mov_b64_e32 v[38:39], v[74:75]
	v_lshl_add_u64 v[46:47], v[22:23], 0, v[20:21]
	v_lshl_add_u64 v[22:23], v[22:23], 0, s[2:3]
	v_and_b32_e32 v41, 0xffff0000, v32
	v_and_b32_e32 v40, 0xffff0000, v34
	v_lshlrev_b32_e32 v31, 16, v32
	v_lshlrev_b32_e32 v30, 16, v34
	v_lshlrev_b32_e32 v42, 16, v35
	v_and_b32_e32 v32, 0xffff0000, v35
	v_lshlrev_b32_e32 v35, 16, v36
	v_lshlrev_b32_e32 v34, 16, v38
	v_and_b32_e32 v45, 0xffff0000, v36
	v_and_b32_e32 v44, 0xffff0000, v38
	v_lshlrev_b32_e32 v48, 16, v39
	v_and_b32_e32 v36, 0xffff0000, v39
	v_pk_mul_f32 v[38:39], v[40:41], v[40:41]
	v_lshlrev_b32_e32 v43, 16, v33
	v_pk_mul_f32 v[50:51], v[44:45], v[44:45]
	v_mov_b32_e32 v52, v30
	v_mov_b32_e32 v53, v40
	v_mov_b32_e32 v40, v31
	v_pk_fma_f32 v[30:31], v[30:31], v[30:31], v[38:39]
	v_and_b32_e32 v33, 0xffff0000, v33
	v_lshlrev_b32_e32 v49, 16, v37
	v_mov_b32_e32 v56, v34
	v_mov_b32_e32 v57, v44
	v_mov_b32_e32 v44, v35
	v_pk_fma_f32 v[34:35], v[34:35], v[34:35], v[50:51]
	v_pk_fma_f32 v[30:31], v[42:43], v[42:43], v[30:31]
	v_and_b32_e32 v37, 0xffff0000, v37
	v_pk_fma_f32 v[34:35], v[48:49], v[48:49], v[34:35]
	v_pk_fma_f32 v[30:31], v[32:33], v[32:33], v[30:31]
	v_pk_fma_f32 v[34:35], v[36:37], v[36:37], v[34:35]
	v_add_f32_e32 v30, v30, v31
	v_add_f32_e32 v30, v30, v34
	v_add_f32_e32 v30, v30, v35
	ds_bpermute_b32 v31, v24, v30
	v_mov_b32_e32 v54, v42
	v_mov_b32_e32 v55, v32
	v_mov_b32_e32 v58, v48
	v_mov_b32_e32 v59, v36
	s_waitcnt lgkmcnt(0)
	v_add_f32_e32 v30, v30, v31
	ds_bpermute_b32 v31, v25, v30
	v_mov_b32_e32 v32, v43
	v_mov_b32_e32 v36, v49
	s_waitcnt lgkmcnt(0)
	v_add_f32_e32 v30, v30, v31
	ds_bpermute_b32 v31, v26, v30
	s_waitcnt lgkmcnt(0)
	v_add_f32_e32 v30, v30, v31
	ds_bpermute_b32 v31, v27, v30
	s_waitcnt lgkmcnt(0)
	v_add_f32_e32 v30, v30, v31
	ds_bpermute_b32 v31, v28, v30
	s_waitcnt lgkmcnt(0)
	v_add_f32_e32 v30, v30, v31
	ds_bpermute_b32 v31, v29, v30
	s_waitcnt lgkmcnt(0)
	v_add_f32_e32 v30, v30, v31
	v_fmamk_f32 v30, v30, 0x3a800000, v17
	v_mul_f32_e32 v31, 0x4b800000, v30
	v_cmp_gt_f32_e32 vcc, s1, v30
	s_nop 1
	v_cndmask_b32_e32 v30, v30, v31, vcc
	v_rsq_f32_e32 v30, v30
	s_nop 0
	v_mul_f32_e32 v31, 0x45800000, v30
	v_cndmask_b32_e32 v30, v30, v31, vcc
	v_pk_mul_f32 v[34:35], v[52:53], v[30:31] op_sel_hi:[1,0]
	v_pk_mul_f32 v[38:39], v[54:55], v[30:31] op_sel_hi:[1,0]
	v_pk_mul_f32 v[40:41], v[40:41], v[30:31] op_sel_hi:[1,0]
	v_pk_mul_f32 v[42:43], v[32:33], v[30:31] op_sel_hi:[1,0]
	v_pk_mul_f32 v[48:49], v[56:57], v[30:31] op_sel_hi:[1,0]
	v_pk_mul_f32 v[50:51], v[58:59], v[30:31] op_sel_hi:[1,0]
	v_pk_mul_f32 v[52:53], v[44:45], v[30:31] op_sel_hi:[1,0]
	v_pk_mul_f32 v[44:45], v[36:37], v[30:31] op_sel_hi:[1,0]
	v_pk_mul_f32 v[32:33], v[2:3], v[38:39]
	v_pk_mul_f32 v[30:31], v[0:1], v[34:35]
	v_pk_mul_f32 v[36:37], v[6:7], v[42:43]
	v_pk_mul_f32 v[34:35], v[4:5], v[40:41]
	v_pk_mul_f32 v[40:41], v[10:11], v[50:51]
	v_pk_mul_f32 v[38:39], v[8:9], v[48:49]
	v_pk_mul_f32 v[44:45], v[14:15], v[44:45]
	v_pk_mul_f32 v[42:43], v[12:13], v[52:53]
	global_store_dwordx4 v[46:47], v[30:33], off
	global_store_dwordx4 v[46:47], v[34:37], off offset:1024
	global_store_dwordx4 v[46:47], v[38:41], off offset:2048
	global_store_dwordx4 v[46:47], v[42:45], off offset:3072
	s_nop 1
	s_waitcnt vmcnt(12)
	v_mov_b64_e32 v[32:33], v[76:77]
	v_mov_b64_e32 v[34:35], v[78:79]
	v_mov_b64_e32 v[36:37], v[80:81]
	v_mov_b64_e32 v[38:39], v[82:83]
	v_lshl_add_u64 v[46:47], v[22:23], 0, v[20:21]
	v_lshl_add_u64 v[22:23], v[22:23], 0, s[2:3]
	v_and_b32_e32 v41, 0xffff0000, v32
	v_and_b32_e32 v40, 0xffff0000, v34
	v_lshlrev_b32_e32 v31, 16, v32
	v_lshlrev_b32_e32 v30, 16, v34
	v_lshlrev_b32_e32 v42, 16, v35
	v_and_b32_e32 v32, 0xffff0000, v35
	v_lshlrev_b32_e32 v35, 16, v36
	v_lshlrev_b32_e32 v34, 16, v38
	v_and_b32_e32 v45, 0xffff0000, v36
	v_and_b32_e32 v44, 0xffff0000, v38
	v_lshlrev_b32_e32 v48, 16, v39
	v_and_b32_e32 v36, 0xffff0000, v39
	v_pk_mul_f32 v[38:39], v[40:41], v[40:41]
	v_lshlrev_b32_e32 v43, 16, v33
	v_pk_mul_f32 v[50:51], v[44:45], v[44:45]
	v_mov_b32_e32 v52, v30
	v_mov_b32_e32 v53, v40
	v_mov_b32_e32 v40, v31
	v_pk_fma_f32 v[30:31], v[30:31], v[30:31], v[38:39]
	v_and_b32_e32 v33, 0xffff0000, v33
	v_lshlrev_b32_e32 v49, 16, v37
	v_mov_b32_e32 v56, v34
	v_mov_b32_e32 v57, v44
	v_mov_b32_e32 v44, v35
	v_pk_fma_f32 v[34:35], v[34:35], v[34:35], v[50:51]
	v_pk_fma_f32 v[30:31], v[42:43], v[42:43], v[30:31]
	v_and_b32_e32 v37, 0xffff0000, v37
	v_pk_fma_f32 v[34:35], v[48:49], v[48:49], v[34:35]
	v_pk_fma_f32 v[30:31], v[32:33], v[32:33], v[30:31]
	v_pk_fma_f32 v[34:35], v[36:37], v[36:37], v[34:35]
	v_add_f32_e32 v30, v30, v31
	v_add_f32_e32 v30, v30, v34
	v_add_f32_e32 v30, v30, v35
	ds_bpermute_b32 v31, v24, v30
	v_mov_b32_e32 v54, v42
	v_mov_b32_e32 v55, v32
	v_mov_b32_e32 v58, v48
	v_mov_b32_e32 v59, v36
	s_waitcnt lgkmcnt(0)
	v_add_f32_e32 v30, v30, v31
	ds_bpermute_b32 v31, v25, v30
	v_mov_b32_e32 v32, v43
	v_mov_b32_e32 v36, v49
	s_waitcnt lgkmcnt(0)
	v_add_f32_e32 v30, v30, v31
	ds_bpermute_b32 v31, v26, v30
	s_waitcnt lgkmcnt(0)
	v_add_f32_e32 v30, v30, v31
	ds_bpermute_b32 v31, v27, v30
	s_waitcnt lgkmcnt(0)
	v_add_f32_e32 v30, v30, v31
	ds_bpermute_b32 v31, v28, v30
	s_waitcnt lgkmcnt(0)
	v_add_f32_e32 v30, v30, v31
	ds_bpermute_b32 v31, v29, v30
	s_waitcnt lgkmcnt(0)
	v_add_f32_e32 v30, v30, v31
	v_fmamk_f32 v30, v30, 0x3a800000, v17
	v_mul_f32_e32 v31, 0x4b800000, v30
	v_cmp_gt_f32_e32 vcc, s1, v30
	s_nop 1
	v_cndmask_b32_e32 v30, v30, v31, vcc
	v_rsq_f32_e32 v30, v30
	s_nop 0
	v_mul_f32_e32 v31, 0x45800000, v30
	v_cndmask_b32_e32 v30, v30, v31, vcc
	v_pk_mul_f32 v[34:35], v[52:53], v[30:31] op_sel_hi:[1,0]
	v_pk_mul_f32 v[38:39], v[54:55], v[30:31] op_sel_hi:[1,0]
	v_pk_mul_f32 v[40:41], v[40:41], v[30:31] op_sel_hi:[1,0]
	v_pk_mul_f32 v[42:43], v[32:33], v[30:31] op_sel_hi:[1,0]
	v_pk_mul_f32 v[48:49], v[56:57], v[30:31] op_sel_hi:[1,0]
	v_pk_mul_f32 v[50:51], v[58:59], v[30:31] op_sel_hi:[1,0]
	v_pk_mul_f32 v[52:53], v[44:45], v[30:31] op_sel_hi:[1,0]
	v_pk_mul_f32 v[44:45], v[36:37], v[30:31] op_sel_hi:[1,0]
	v_pk_mul_f32 v[32:33], v[2:3], v[38:39]
	v_pk_mul_f32 v[30:31], v[0:1], v[34:35]
	v_pk_mul_f32 v[36:37], v[6:7], v[42:43]
	v_pk_mul_f32 v[34:35], v[4:5], v[40:41]
	v_pk_mul_f32 v[40:41], v[10:11], v[50:51]
	v_pk_mul_f32 v[38:39], v[8:9], v[48:49]
	v_pk_mul_f32 v[44:45], v[14:15], v[44:45]
	v_pk_mul_f32 v[42:43], v[12:13], v[52:53]
	global_store_dwordx4 v[46:47], v[30:33], off
	global_store_dwordx4 v[46:47], v[34:37], off offset:1024
	global_store_dwordx4 v[46:47], v[38:41], off offset:2048
	global_store_dwordx4 v[46:47], v[42:45], off offset:3072
	s_nop 1
	s_waitcnt vmcnt(12)
	v_mov_b64_e32 v[32:33], v[84:85]
	v_mov_b64_e32 v[34:35], v[86:87]
	v_mov_b64_e32 v[36:37], v[88:89]
	v_mov_b64_e32 v[38:39], v[90:91]
	v_lshl_add_u64 v[46:47], v[22:23], 0, v[20:21]
	v_lshl_add_u64 v[22:23], v[22:23], 0, s[2:3]
	v_and_b32_e32 v41, 0xffff0000, v32
	v_and_b32_e32 v40, 0xffff0000, v34
	v_lshlrev_b32_e32 v31, 16, v32
	v_lshlrev_b32_e32 v30, 16, v34
	v_lshlrev_b32_e32 v42, 16, v35
	v_and_b32_e32 v32, 0xffff0000, v35
	v_lshlrev_b32_e32 v35, 16, v36
	v_lshlrev_b32_e32 v34, 16, v38
	v_and_b32_e32 v45, 0xffff0000, v36
	v_and_b32_e32 v44, 0xffff0000, v38
	v_lshlrev_b32_e32 v48, 16, v39
	v_and_b32_e32 v36, 0xffff0000, v39
	v_pk_mul_f32 v[38:39], v[40:41], v[40:41]
	v_lshlrev_b32_e32 v43, 16, v33
	v_pk_mul_f32 v[50:51], v[44:45], v[44:45]
	v_mov_b32_e32 v52, v30
	v_mov_b32_e32 v53, v40
	v_mov_b32_e32 v40, v31
	v_pk_fma_f32 v[30:31], v[30:31], v[30:31], v[38:39]
	v_and_b32_e32 v33, 0xffff0000, v33
	v_lshlrev_b32_e32 v49, 16, v37
	v_mov_b32_e32 v56, v34
	v_mov_b32_e32 v57, v44
	v_mov_b32_e32 v44, v35
	v_pk_fma_f32 v[34:35], v[34:35], v[34:35], v[50:51]
	v_pk_fma_f32 v[30:31], v[42:43], v[42:43], v[30:31]
	v_and_b32_e32 v37, 0xffff0000, v37
	v_pk_fma_f32 v[34:35], v[48:49], v[48:49], v[34:35]
	v_pk_fma_f32 v[30:31], v[32:33], v[32:33], v[30:31]
	v_pk_fma_f32 v[34:35], v[36:37], v[36:37], v[34:35]
	v_add_f32_e32 v30, v30, v31
	v_add_f32_e32 v30, v30, v34
	v_add_f32_e32 v30, v30, v35
	ds_bpermute_b32 v31, v24, v30
	v_mov_b32_e32 v54, v42
	v_mov_b32_e32 v55, v32
	v_mov_b32_e32 v58, v48
	v_mov_b32_e32 v59, v36
	s_waitcnt lgkmcnt(0)
	v_add_f32_e32 v30, v30, v31
	ds_bpermute_b32 v31, v25, v30
	v_mov_b32_e32 v32, v43
	v_mov_b32_e32 v36, v49
	s_waitcnt lgkmcnt(0)
	v_add_f32_e32 v30, v30, v31
	ds_bpermute_b32 v31, v26, v30
	s_waitcnt lgkmcnt(0)
	v_add_f32_e32 v30, v30, v31
	ds_bpermute_b32 v31, v27, v30
	s_waitcnt lgkmcnt(0)
	v_add_f32_e32 v30, v30, v31
	ds_bpermute_b32 v31, v28, v30
	s_waitcnt lgkmcnt(0)
	v_add_f32_e32 v30, v30, v31
	ds_bpermute_b32 v31, v29, v30
	s_waitcnt lgkmcnt(0)
	v_add_f32_e32 v30, v30, v31
	v_fmamk_f32 v30, v30, 0x3a800000, v17
	v_mul_f32_e32 v31, 0x4b800000, v30
	v_cmp_gt_f32_e32 vcc, s1, v30
	s_nop 1
	v_cndmask_b32_e32 v30, v30, v31, vcc
	v_rsq_f32_e32 v30, v30
	s_nop 0
	v_mul_f32_e32 v31, 0x45800000, v30
	v_cndmask_b32_e32 v30, v30, v31, vcc
	v_pk_mul_f32 v[34:35], v[52:53], v[30:31] op_sel_hi:[1,0]
	v_pk_mul_f32 v[38:39], v[54:55], v[30:31] op_sel_hi:[1,0]
	v_pk_mul_f32 v[40:41], v[40:41], v[30:31] op_sel_hi:[1,0]
	v_pk_mul_f32 v[42:43], v[32:33], v[30:31] op_sel_hi:[1,0]
	v_pk_mul_f32 v[48:49], v[56:57], v[30:31] op_sel_hi:[1,0]
	v_pk_mul_f32 v[50:51], v[58:59], v[30:31] op_sel_hi:[1,0]
	v_pk_mul_f32 v[52:53], v[44:45], v[30:31] op_sel_hi:[1,0]
	v_pk_mul_f32 v[44:45], v[36:37], v[30:31] op_sel_hi:[1,0]
	v_pk_mul_f32 v[32:33], v[2:3], v[38:39]
	v_pk_mul_f32 v[30:31], v[0:1], v[34:35]
	v_pk_mul_f32 v[36:37], v[6:7], v[42:43]
	v_pk_mul_f32 v[34:35], v[4:5], v[40:41]
	v_pk_mul_f32 v[40:41], v[10:11], v[50:51]
	v_pk_mul_f32 v[38:39], v[8:9], v[48:49]
	v_pk_mul_f32 v[44:45], v[14:15], v[44:45]
	v_pk_mul_f32 v[42:43], v[12:13], v[52:53]
	global_store_dwordx4 v[46:47], v[30:33], off
	global_store_dwordx4 v[46:47], v[34:37], off offset:1024
	global_store_dwordx4 v[46:47], v[38:41], off offset:2048
	global_store_dwordx4 v[46:47], v[42:45], off offset:3072
	s_nop 1
	s_lshl_b32 s9, s0, 2
	v_add_u32_e32 v16, s9, v16
	s_add_i32 s8, s8, s9
	s_branch .Lfin_fast
.Lfin_tail:
	s_cmp_lt_i32 s8, 0x8000
	s_cbranch_scc0 .LBB0_1474
